# grid barrier: acquire-side buffer_inv issued right after arrival (CU issues no cacheable loads until release) instead of after the release is observed
# speedup vs baseline: 1.0120x; 1.0061x over previous
; DI unsigned xb_ld(unsigned* p) { return __hip_atomic_load(p, __ATOMIC_RELAXED, __HIP_MEMORY_SCOPE_AGENT); }
; DI unsigned xb_add(unsigned* p, unsigned v) { return __hip_atomic_fetch_add(p, v, __ATOMIC_RELAXED, __HIP_MEMORY_SCOPE_AGENT); }
; #define XB_SPIN(cond, bar) do { unsigned _sp = 0; while (cond) { __builtin_amdgcn_s_sleep(1); \
;     if ((++_sp & 255u) == 0u) { if (xb_ld(&(bar)[XB_TMO])) break; if (_sp > XB_SPIN_CAP) { atomicAdd(&(bar)[XB_TMO], 1u); break; } } } } while (0)
; DI void xcd_barrier(const XcdBarrier& b) {
;     ...
;     const unsigned old = xb_add(&bar[XB_XSUB(b.x)], 1u);
;     const unsigned gen = old / nloc;
;     if (old + 1u == (gen + 1u) * nloc) {
;       __builtin_amdgcn_fence(__ATOMIC_RELEASE, "agent");
;       asm volatile("s_waitcnt vmcnt(0)" ::: "memory");
;       const unsigned og = xb_add(&bar[XB_TOP], 1u);
;       const unsigned tg = og / nx;
;       if (og + 1u == (tg + 1u) * nx) xb_add(&bar[XB_TOPGEN], 1u);
;       else XB_SPIN(xb_ld(&bar[XB_TOPGEN]) == tg, bar);
;       __builtin_amdgcn_fence(__ATOMIC_ACQUIRE, "agent");
;       xb_add(&bar[XB_XGEN(b.x)], 1u);
;       asm volatile("s_waitcnt vmcnt(0)" ::: "memory");
;     } else {
;       XB_SPIN(xb_ld(&bar[XB_XGEN(b.x)]) == gen, bar);
.LBB0_147:
	s_or_b64 exec, exec, s[2:3]
	v_cvt_f32_u32_e32 v4, v2
	s_waitcnt vmcnt(0)
	v_readfirstlane_b32 s2, v3
	buffer_inv sc1
	v_sub_u32_e32 v3, 0, v2
	v_rcp_iflag_f32_e32 v4, v4
	v_add_u32_e32 v5, s2, v1
	v_mul_f32_e32 v4, 0x4f7ffffe, v4
	v_cvt_u32_f32_e32 v4, v4
	v_mul_lo_u32 v1, v3, v4
	v_mul_hi_u32 v1, v4, v1
	v_add_u32_e32 v1, v4, v1
	v_mul_hi_u32 v1, v5, v1
	v_mul_lo_u32 v3, v1, v2
	v_sub_u32_e32 v3, v5, v3
	v_add_u32_e32 v4, 1, v1
	v_cmp_ge_u32_e32 vcc, v3, v2
	s_nop 1
	v_cndmask_b32_e32 v1, v1, v4, vcc
	v_sub_u32_e32 v4, v3, v2
	v_cndmask_b32_e32 v3, v3, v4, vcc
	v_add_u32_e32 v4, 1, v1
	v_cmp_ge_u32_e32 vcc, v3, v2
	v_add_u32_e32 v3, 1, v5
	s_nop 0
	v_cndmask_b32_e32 v1, v1, v4, vcc
	v_mul_lo_u32 v4, v2, v1
	v_add_u32_e32 v2, v4, v2
	v_cmp_ne_u32_e32 vcc, v3, v2
	s_and_saveexec_b64 s[2:3], vcc
	s_xor_b64 s[2:3], exec, s[2:3]
	s_cbranch_execz .LBB0_161
	v_readlane_b32 s4, v253, 21
	s_waitcnt lgkmcnt(0)
	v_mov_b32_e32 v0, 0
	v_readlane_b32 s5, v253, 22
	s_nop 4
	global_load_dword v2, v0, s[4:5] sc1
	s_waitcnt vmcnt(0)
	v_cmp_eq_u32_e32 vcc, v2, v1
	s_and_saveexec_b64 s[4:5], vcc
	s_cbranch_execz .LBB0_160
	s_mov_b32 s16, 1
	s_mov_b64 s[6:7], 0
	s_branch .LBB0_151

; DI unsigned xb_ld(unsigned* p) { return __hip_atomic_load(p, __ATOMIC_RELAXED, __HIP_MEMORY_SCOPE_AGENT); }
; #define XB_SPIN(cond, bar) do { unsigned _sp = 0; while (cond) { __builtin_amdgcn_s_sleep(1); \
;     if ((++_sp & 255u) == 0u) { if (xb_ld(&(bar)[XB_TMO])) break; if (_sp > XB_SPIN_CAP) { atomicAdd(&(bar)[XB_TMO], 1u); break; } } } } while (0)
; DI void xcd_barrier(const XcdBarrier& b) {
;     ...
;       XB_SPIN(xb_ld(&bar[XB_XGEN(b.x)]) == gen, bar);
;       __builtin_amdgcn_fence(__ATOMIC_ACQUIRE, "agent");
;       asm volatile("s_waitcnt vmcnt(0)" ::: "memory");
.LBB0_160:
	s_or_b64 exec, exec, s[4:5]
	s_waitcnt vmcnt(0)
	s_waitcnt vmcnt(0)

; DI unsigned xb_ld(unsigned* p) { return __hip_atomic_load(p, __ATOMIC_RELAXED, __HIP_MEMORY_SCOPE_AGENT); }
; DI unsigned xb_add(unsigned* p, unsigned v) { return __hip_atomic_fetch_add(p, v, __ATOMIC_RELAXED, __HIP_MEMORY_SCOPE_AGENT); }
; #define XB_SPIN(cond, bar) do { unsigned _sp = 0; while (cond) { __builtin_amdgcn_s_sleep(1); \
;     if ((++_sp & 255u) == 0u) { if (xb_ld(&(bar)[XB_TMO])) break; if (_sp > XB_SPIN_CAP) { atomicAdd(&(bar)[XB_TMO], 1u); break; } } } } while (0)
; DI void xcd_barrier(const XcdBarrier& b) {
;     ...
;       if (og + 1u == (tg + 1u) * nx) xb_add(&bar[XB_TOPGEN], 1u);
;       else XB_SPIN(xb_ld(&bar[XB_TOPGEN]) == tg, bar);
;       __builtin_amdgcn_fence(__ATOMIC_ACQUIRE, "agent");
;       xb_add(&bar[XB_XGEN(b.x)], 1u);
.LBB0_178:
	s_or_b64 exec, exec, s[2:3]
	s_mov_b64 s[2:3], exec
	v_mbcnt_lo_u32_b32 v0, s2, 0
	v_mbcnt_hi_u32_b32 v0, s3, v0
	v_cmp_eq_u32_e32 vcc, 0, v0
	s_waitcnt vmcnt(0)
	s_and_saveexec_b64 s[4:5], vcc
	s_cbranch_execz .LBB0_180
	s_bcnt1_i32_b64 s2, s[2:3]
	v_mov_b32_e32 v1, s2
	v_readlane_b32 s2, v253, 21
	v_mov_b32_e32 v0, 0
	v_readlane_b32 s3, v253, 22
	s_nop 4
	global_atomic_add v0, v1, s[2:3]

; DI unsigned xb_ld(unsigned* p) { return __hip_atomic_load(p, __ATOMIC_RELAXED, __HIP_MEMORY_SCOPE_AGENT); }
; DI unsigned xb_add(unsigned* p, unsigned v) { return __hip_atomic_fetch_add(p, v, __ATOMIC_RELAXED, __HIP_MEMORY_SCOPE_AGENT); }
; #define XB_SPIN(cond, bar) do { unsigned _sp = 0; while (cond) { __builtin_amdgcn_s_sleep(1); \
;     if ((++_sp & 255u) == 0u) { if (xb_ld(&(bar)[XB_TMO])) break; if (_sp > XB_SPIN_CAP) { atomicAdd(&(bar)[XB_TMO], 1u); break; } } } } while (0)
; DI void xcd_barrier(const XcdBarrier& b) {
;     ...
;     const unsigned old = xb_add(&bar[XB_XSUB(b.x)], 1u);
;     const unsigned gen = old / nloc;
;     if (old + 1u == (gen + 1u) * nloc) {
;       __builtin_amdgcn_fence(__ATOMIC_RELEASE, "agent");
;       asm volatile("s_waitcnt vmcnt(0)" ::: "memory");
;       const unsigned og = xb_add(&bar[XB_TOP], 1u);
;       const unsigned tg = og / nx;
;       if (og + 1u == (tg + 1u) * nx) xb_add(&bar[XB_TOPGEN], 1u);
;       else XB_SPIN(xb_ld(&bar[XB_TOPGEN]) == tg, bar);
;       __builtin_amdgcn_fence(__ATOMIC_ACQUIRE, "agent");
;       xb_add(&bar[XB_XGEN(b.x)], 1u);
;       asm volatile("s_waitcnt vmcnt(0)" ::: "memory");
;     } else {
;       XB_SPIN(xb_ld(&bar[XB_XGEN(b.x)]) == gen, bar);
.LBB0_508:
	s_or_b64 exec, exec, s[2:3]
	v_cvt_f32_u32_e32 v5, v3
	s_waitcnt vmcnt(0)
	v_readfirstlane_b32 s2, v4
	buffer_inv sc1
	v_sub_u32_e32 v4, 0, v3
	v_rcp_iflag_f32_e32 v5, v5
	v_add_u32_e32 v6, s2, v1
	v_mul_f32_e32 v5, 0x4f7ffffe, v5
	v_cvt_u32_f32_e32 v5, v5
	v_mul_lo_u32 v1, v4, v5
	v_mul_hi_u32 v1, v5, v1
	v_add_u32_e32 v1, v5, v1
	v_mul_hi_u32 v1, v6, v1
	v_mul_lo_u32 v4, v1, v3
	v_sub_u32_e32 v4, v6, v4
	v_add_u32_e32 v5, 1, v1
	v_cmp_ge_u32_e32 vcc, v4, v3
	s_nop 1
	v_cndmask_b32_e32 v1, v1, v5, vcc
	v_sub_u32_e32 v5, v4, v3
	v_cndmask_b32_e32 v4, v4, v5, vcc
	v_add_u32_e32 v5, 1, v1
	v_cmp_ge_u32_e32 vcc, v4, v3
	v_add_u32_e32 v4, 1, v6
	s_nop 0
	v_cndmask_b32_e32 v1, v1, v5, vcc
	v_mul_lo_u32 v5, v3, v1
	v_add_u32_e32 v3, v5, v3
	v_cmp_ne_u32_e32 vcc, v4, v3
	s_and_saveexec_b64 s[2:3], vcc
	s_xor_b64 s[2:3], exec, s[2:3]
	s_cbranch_execz .LBB0_522
	v_readlane_b32 s4, v253, 21
	v_readlane_b32 s5, v253, 22
	s_waitcnt lgkmcnt(0)
	s_nop 3
	global_load_dword v0, v2, s[4:5] sc1
	s_waitcnt vmcnt(0)
	v_cmp_eq_u32_e32 vcc, v0, v1
	s_and_saveexec_b64 s[4:5], vcc
	s_cbranch_execz .LBB0_521
	s_mov_b32 s7, 1
	s_mov_b64 s[12:13], 0
	s_branch .LBB0_512

; DI unsigned xb_ld(unsigned* p) { return __hip_atomic_load(p, __ATOMIC_RELAXED, __HIP_MEMORY_SCOPE_AGENT); }
; DI unsigned xb_add(unsigned* p, unsigned v) { return __hip_atomic_fetch_add(p, v, __ATOMIC_RELAXED, __HIP_MEMORY_SCOPE_AGENT); }
; #define XB_SPIN(cond, bar) do { unsigned _sp = 0; while (cond) { __builtin_amdgcn_s_sleep(1); \
;     if ((++_sp & 255u) == 0u) { if (xb_ld(&(bar)[XB_TMO])) break; if (_sp > XB_SPIN_CAP) { atomicAdd(&(bar)[XB_TMO], 1u); break; } } } } while (0)
; DI void xcd_barrier(const XcdBarrier& b) {
;     ...
;       if (og + 1u == (tg + 1u) * nx) xb_add(&bar[XB_TOPGEN], 1u);
;       else XB_SPIN(xb_ld(&bar[XB_TOPGEN]) == tg, bar);
;       __builtin_amdgcn_fence(__ATOMIC_ACQUIRE, "agent");
;       xb_add(&bar[XB_XGEN(b.x)], 1u);
.LBB0_539:
	s_or_b64 exec, exec, s[2:3]
	s_mov_b64 s[2:3], exec
	v_mbcnt_lo_u32_b32 v0, s2, 0
	v_mbcnt_hi_u32_b32 v0, s3, v0
	v_cmp_eq_u32_e32 vcc, 0, v0
	s_waitcnt vmcnt(0)
	s_and_saveexec_b64 s[4:5], vcc
	s_cbranch_execz .LBB0_541
	s_bcnt1_i32_b64 s2, s[2:3]
	v_mov_b32_e32 v0, s2
	v_readlane_b32 s2, v253, 21
	v_readlane_b32 s3, v253, 22
	s_nop 4
	global_atomic_add v2, v0, s[2:3]

; DI unsigned xb_ld(unsigned* p) { return __hip_atomic_load(p, __ATOMIC_RELAXED, __HIP_MEMORY_SCOPE_AGENT); }
; DI unsigned xb_add(unsigned* p, unsigned v) { return __hip_atomic_fetch_add(p, v, __ATOMIC_RELAXED, __HIP_MEMORY_SCOPE_AGENT); }
; #define XB_SPIN(cond, bar) do { unsigned _sp = 0; while (cond) { __builtin_amdgcn_s_sleep(1); \
;     if ((++_sp & 255u) == 0u) { if (xb_ld(&(bar)[XB_TMO])) break; if (_sp > XB_SPIN_CAP) { atomicAdd(&(bar)[XB_TMO], 1u); break; } } } } while (0)
; DI void xcd_barrier(const XcdBarrier& b) {
;     ...
;     const unsigned old = xb_add(&bar[XB_XSUB(b.x)], 1u);
;     const unsigned gen = old / nloc;
;     if (old + 1u == (gen + 1u) * nloc) {
;       __builtin_amdgcn_fence(__ATOMIC_RELEASE, "agent");
;       asm volatile("s_waitcnt vmcnt(0)" ::: "memory");
;       const unsigned og = xb_add(&bar[XB_TOP], 1u);
;       const unsigned tg = og / nx;
;       if (og + 1u == (tg + 1u) * nx) xb_add(&bar[XB_TOPGEN], 1u);
;       else XB_SPIN(xb_ld(&bar[XB_TOPGEN]) == tg, bar);
;       __builtin_amdgcn_fence(__ATOMIC_ACQUIRE, "agent");
;       xb_add(&bar[XB_XGEN(b.x)], 1u);
;       asm volatile("s_waitcnt vmcnt(0)" ::: "memory");
;     } else {
;       XB_SPIN(xb_ld(&bar[XB_XGEN(b.x)]) == gen, bar);
.LBB0_596:
	s_or_b64 exec, exec, s[2:3]
	v_cvt_f32_u32_e32 v5, v3
	s_waitcnt vmcnt(0)
	v_readfirstlane_b32 s2, v4
	buffer_inv sc1
	v_sub_u32_e32 v4, 0, v3
	v_rcp_iflag_f32_e32 v5, v5
	v_add_u32_e32 v6, s2, v1
	v_mul_f32_e32 v5, 0x4f7ffffe, v5
	v_cvt_u32_f32_e32 v5, v5
	v_mul_lo_u32 v1, v4, v5
	v_mul_hi_u32 v1, v5, v1
	v_add_u32_e32 v1, v5, v1
	v_mul_hi_u32 v1, v6, v1
	v_mul_lo_u32 v4, v1, v3
	v_sub_u32_e32 v4, v6, v4
	v_add_u32_e32 v5, 1, v1
	v_cmp_ge_u32_e32 vcc, v4, v3
	s_nop 1
	v_cndmask_b32_e32 v1, v1, v5, vcc
	v_sub_u32_e32 v5, v4, v3
	v_cndmask_b32_e32 v4, v4, v5, vcc
	v_add_u32_e32 v5, 1, v1
	v_cmp_ge_u32_e32 vcc, v4, v3
	v_add_u32_e32 v4, 1, v6
	s_nop 0
	v_cndmask_b32_e32 v1, v1, v5, vcc
	v_mul_lo_u32 v5, v3, v1
	v_add_u32_e32 v3, v5, v3
	v_cmp_ne_u32_e32 vcc, v4, v3
	s_and_saveexec_b64 s[2:3], vcc
	s_xor_b64 s[2:3], exec, s[2:3]
	s_cbranch_execz .LBB0_610
	v_readlane_b32 s4, v253, 21
	v_readlane_b32 s5, v253, 22
	s_waitcnt lgkmcnt(0)
	s_nop 3
	global_load_dword v0, v2, s[4:5] sc1
	s_waitcnt vmcnt(0)
	v_cmp_eq_u32_e32 vcc, v0, v1
	s_and_saveexec_b64 s[4:5], vcc
	s_cbranch_execz .LBB0_609
	s_mov_b32 s7, 1
	s_mov_b64 s[8:9], 0
	s_branch .LBB0_600

; DI unsigned xb_ld(unsigned* p) { return __hip_atomic_load(p, __ATOMIC_RELAXED, __HIP_MEMORY_SCOPE_AGENT); }
; DI unsigned xb_add(unsigned* p, unsigned v) { return __hip_atomic_fetch_add(p, v, __ATOMIC_RELAXED, __HIP_MEMORY_SCOPE_AGENT); }
; #define XB_SPIN(cond, bar) do { unsigned _sp = 0; while (cond) { __builtin_amdgcn_s_sleep(1); \
;     if ((++_sp & 255u) == 0u) { if (xb_ld(&(bar)[XB_TMO])) break; if (_sp > XB_SPIN_CAP) { atomicAdd(&(bar)[XB_TMO], 1u); break; } } } } while (0)
; DI void xcd_barrier(const XcdBarrier& b) {
;     ...
;     const unsigned old = xb_add(&bar[XB_XSUB(b.x)], 1u);
;     const unsigned gen = old / nloc;
;     if (old + 1u == (gen + 1u) * nloc) {
;       __builtin_amdgcn_fence(__ATOMIC_RELEASE, "agent");
;       asm volatile("s_waitcnt vmcnt(0)" ::: "memory");
;       const unsigned og = xb_add(&bar[XB_TOP], 1u);
;       const unsigned tg = og / nx;
;       if (og + 1u == (tg + 1u) * nx) xb_add(&bar[XB_TOPGEN], 1u);
;       else XB_SPIN(xb_ld(&bar[XB_TOPGEN]) == tg, bar);
;       __builtin_amdgcn_fence(__ATOMIC_ACQUIRE, "agent");
;       xb_add(&bar[XB_XGEN(b.x)], 1u);
;       asm volatile("s_waitcnt vmcnt(0)" ::: "memory");
;     } else {
;       XB_SPIN(xb_ld(&bar[XB_XGEN(b.x)]) == gen, bar);
.LBB0_868:
	s_or_b64 exec, exec, s[2:3]
	v_cvt_f32_u32_e32 v5, v3
	s_waitcnt vmcnt(0)
	v_readfirstlane_b32 s2, v4
	buffer_inv sc1
	v_sub_u32_e32 v4, 0, v3
	v_rcp_iflag_f32_e32 v5, v5
	v_add_u32_e32 v6, s2, v1
	v_mul_f32_e32 v5, 0x4f7ffffe, v5
	v_cvt_u32_f32_e32 v5, v5
	v_mul_lo_u32 v1, v4, v5
	v_mul_hi_u32 v1, v5, v1
	v_add_u32_e32 v1, v5, v1
	v_mul_hi_u32 v1, v6, v1
	v_mul_lo_u32 v4, v1, v3
	v_sub_u32_e32 v4, v6, v4
	v_add_u32_e32 v5, 1, v1
	v_cmp_ge_u32_e32 vcc, v4, v3
	s_nop 1
	v_cndmask_b32_e32 v1, v1, v5, vcc
	v_sub_u32_e32 v5, v4, v3
	v_cndmask_b32_e32 v4, v4, v5, vcc
	v_add_u32_e32 v5, 1, v1
	v_cmp_ge_u32_e32 vcc, v4, v3
	v_add_u32_e32 v4, 1, v6
	s_nop 0
	v_cndmask_b32_e32 v1, v1, v5, vcc
	v_mul_lo_u32 v5, v3, v1
	v_add_u32_e32 v3, v5, v3
	v_cmp_ne_u32_e32 vcc, v4, v3
	s_and_saveexec_b64 s[2:3], vcc
	s_xor_b64 s[2:3], exec, s[2:3]
	s_cbranch_execz .LBB0_882
	v_readlane_b32 s4, v253, 21
	v_readlane_b32 s5, v253, 22
	s_waitcnt lgkmcnt(0)
	s_nop 3
	global_load_dword v0, v2, s[4:5] sc1
	s_waitcnt vmcnt(0)
	v_cmp_eq_u32_e32 vcc, v0, v1
	s_and_saveexec_b64 s[4:5], vcc
	s_cbranch_execz .LBB0_881
	s_mov_b32 s24, 1
	s_mov_b64 s[6:7], 0
	s_branch .LBB0_872

; DI unsigned xb_ld(unsigned* p) { return __hip_atomic_load(p, __ATOMIC_RELAXED, __HIP_MEMORY_SCOPE_AGENT); }
; DI unsigned xb_add(unsigned* p, unsigned v) { return __hip_atomic_fetch_add(p, v, __ATOMIC_RELAXED, __HIP_MEMORY_SCOPE_AGENT); }
; #define XB_SPIN(cond, bar) do { unsigned _sp = 0; while (cond) { __builtin_amdgcn_s_sleep(1); \
;     if ((++_sp & 255u) == 0u) { if (xb_ld(&(bar)[XB_TMO])) break; if (_sp > XB_SPIN_CAP) { atomicAdd(&(bar)[XB_TMO], 1u); break; } } } } while (0)
; DI void xcd_barrier(const XcdBarrier& b) {
;     ...
;       if (og + 1u == (tg + 1u) * nx) xb_add(&bar[XB_TOPGEN], 1u);
;       else XB_SPIN(xb_ld(&bar[XB_TOPGEN]) == tg, bar);
;       __builtin_amdgcn_fence(__ATOMIC_ACQUIRE, "agent");
;       xb_add(&bar[XB_XGEN(b.x)], 1u);
.LBB0_1411:
	s_or_b64 exec, exec, s[2:3]
	s_mov_b64 s[2:3], exec
	v_mbcnt_lo_u32_b32 v0, s2, 0
	v_mbcnt_hi_u32_b32 v0, s3, v0
	v_cmp_eq_u32_e32 vcc, 0, v0
	s_waitcnt vmcnt(0)
	s_and_saveexec_b64 s[4:5], vcc
	s_cbranch_execnz .LBB0_1412
	s_getpc_b64 s[98:99]
